# scan chunk loops: wait only for loads (vmcnt(16)) instead of draining the 16 output stores, and issue next chunk's loads before barrier 1 (q-gate loads renamed to spare VGPRs)
# speedup vs baseline: 1.0070x; 1.0009x over previous
.LBB0_337:
	s_add_i32 s80, s80, 32
	s_sub_i32 s26, s26, 32
	s_add_i32 s27, s27, 1
	v_subrev_u32_e32 v165, 32, v165
	v_lshl_add_u64 v[144:145], v[144:145], 0, 64
	s_cmpk_lg_i32 s80, 0x400
	v_lshl_add_u64 v[146:147], v[146:147], 0, s[22:23]
	s_cbranch_scc0 .LBB0_394
	s_waitcnt vmcnt(0)
	v_mov_b32_e32 v149, v176
	v_mov_b32_e32 v151, v177
	v_mov_b32_e32 v153, v178
	v_mov_b32_e32 v155, v179
	s_branch .Lscan1_top

.Lscan1_top:
	v_lshlrev_b32_e32 v0, 16, v135
	v_max_f32_e32 v0, v0, v0
	v_max_f32_e64 v4, -v156, -v156
	v_max_f32_e32 v0, v0, v4
	v_max_f32_e32 v5, v156, v156
	v_min_f32_e32 v0, v0, v5
	v_mul_f32_e32 v0, 0xbfb8aa3b, v0
	v_exp_f32_e32 v14, v0
	v_and_b32_e32 v0, 0xffff0000, v135
	v_max_f32_e32 v0, v0, v0
	v_max_f32_e32 v0, v0, v4
	v_min_f32_e32 v0, v0, v5
	v_mul_f32_e32 v0, 0xbfb8aa3b, v0
	v_exp_f32_e32 v15, v0
	v_add_f32_e32 v0, 1.0, v14
	v_rcp_f32_e32 v80, v0
	s_andn2_b64 vcc, exec, s[90:91]
	v_add_f32_e32 v0, 1.0, v15
	v_rcp_f32_e32 v81, v0
	v_pk_fma_f32 v[2:3], v[132:133], v[14:15], 1.0 op_sel_hi:[1,1,0]
	v_lshlrev_b32_e32 v0, 16, v150
	v_max_f32_e32 v0, v0, v0
	v_pk_mul_f32 v[10:11], v[80:81], v[2:3]
	v_lshlrev_b32_e32 v2, 16, v152
	v_max_f32_e32 v2, v2, v2
	v_max_f32_e32 v2, v2, v4
	v_min_f32_e32 v2, v2, v5
	v_mul_f32_e32 v2, 0xbfb8aa3b, v2
	v_exp_f32_e32 v86, v2
	v_and_b32_e32 v2, 0xffff0000, v152
	v_max_f32_e32 v2, v2, v2
	v_max_f32_e32 v2, v2, v4
	v_max_f32_e32 v0, v0, v4
	v_min_f32_e32 v2, v2, v5
	v_min_f32_e32 v0, v0, v5
	v_mul_f32_e32 v2, 0xbfb8aa3b, v2
	v_mul_f32_e32 v0, 0xbfb8aa3b, v0
	v_exp_f32_e32 v87, v2
	v_lshlrev_b32_e32 v2, 16, v154
	v_exp_f32_e32 v82, v0
	v_and_b32_e32 v0, 0xffff0000, v150
	v_max_f32_e32 v2, v2, v2
	v_max_f32_e32 v0, v0, v0
	v_max_f32_e32 v2, v2, v4
	v_max_f32_e32 v0, v0, v4
	v_min_f32_e32 v2, v2, v5
	v_min_f32_e32 v0, v0, v5
	v_mul_f32_e32 v2, 0xbfb8aa3b, v2
	v_mul_f32_e32 v0, 0xbfb8aa3b, v0
	v_exp_f32_e32 v90, v2
	v_and_b32_e32 v2, 0xffff0000, v154
	v_exp_f32_e32 v83, v0
	v_max_f32_e32 v2, v2, v2
	v_max_f32_e32 v2, v2, v4
	v_min_f32_e32 v2, v2, v5
	v_add_f32_e32 v0, 1.0, v82
	v_mul_f32_e32 v2, 0xbfb8aa3b, v2
	v_rcp_f32_e32 v84, v0
	v_add_f32_e32 v0, 1.0, v83
	v_exp_f32_e32 v91, v2
	v_rcp_f32_e32 v85, v0
	v_add_f32_e32 v0, 1.0, v86
	v_rcp_f32_e32 v88, v0
	v_add_f32_e32 v0, 1.0, v87
	v_rcp_f32_e32 v89, v0
	v_add_f32_e32 v0, 1.0, v90
	v_rcp_f32_e32 v92, v0
	v_add_f32_e32 v0, 1.0, v91
	v_pk_fma_f32 v[2:3], v[132:133], v[82:83], 1.0 op_sel_hi:[1,1,0]
	v_rcp_f32_e32 v93, v0
	v_pk_mul_f32 v[2:3], v[84:85], v[2:3]
	s_nop 0
	v_pk_mul_f32 v[12:13], v[10:11], v[2:3]
	v_pk_fma_f32 v[2:3], v[132:133], v[86:87], 1.0 op_sel_hi:[1,1,0]
	s_nop 0
	v_pk_mul_f32 v[2:3], v[88:89], v[2:3]
	s_nop 0
	v_pk_mul_f32 v[8:9], v[12:13], v[2:3]
	v_pk_fma_f32 v[2:3], v[132:133], v[90:91], 1.0 op_sel_hi:[1,1,0]
	s_nop 0
	v_pk_mul_f32 v[2:3], v[92:93], v[2:3]
	s_nop 0
	v_pk_mul_f32 v[6:7], v[8:9], v[2:3]
	v_mov_b64_e32 v[2:3], v[128:129]
	v_mov_b64_e32 v[4:5], v[130:131]
	ds_write_b64 v157, v[6:7] offset:46848
	s_cbranch_vccnz .LBB0_340
	v_alignbit_b32 v2, v131, v131, 16
	v_alignbit_b32 v3, v130, v130, 16
	v_alignbit_b32 v4, v129, v129, 16
	v_alignbit_b32 v5, v128, v128, 16
.LBB0_340:
	v_add_u32_e32 v0, v158, v134
	ds_write_b128 v166, v[2:5] offset:36096
	s_cmp_gt_u32 s27, 30
	s_cbranch_scc1 .Lscan1_top_nold
	s_add_i32 s89, s21, s80
	s_add_i32 s93, s89, 32
	s_and_b64 s[72:73], s[38:39], exec
	s_cselect_b32 s72, s93, s26
	s_ashr_i32 s73, s72, 31
	s_lshl_b64 s[72:73], s[72:73], 14
	v_lshl_add_u64 v[180:181], v[138:139], 0, s[72:73]
	global_load_dword v135, v[180:181], off
	v_lshl_add_u64 v[180:181], v[136:137], 0, s[72:73]
	s_xor_b32 s72, s93, -2
	s_add_i32 s96, s89, 33
	s_add_i32 s97, s72, 0x400
	s_and_b64 s[72:73], s[38:39], exec
	s_cselect_b32 s72, s96, s97
	s_ashr_i32 s73, s72, 31
	s_lshl_b64 s[72:73], s[72:73], 14
	global_load_dword v176, v[180:181], off
	v_lshl_add_u64 v[180:181], v[138:139], 0, s[72:73]
	global_load_dword v150, v[180:181], off
	v_lshl_add_u64 v[180:181], v[136:137], 0, s[72:73]
	s_xor_b32 s72, s93, -3
	s_add_i32 s96, s89, 34
	s_add_i32 s97, s72, 0x400
	s_and_b64 s[72:73], s[38:39], exec
	s_cselect_b32 s72, s96, s97
	s_ashr_i32 s73, s72, 31
	s_lshl_b64 s[72:73], s[72:73], 14
	global_load_dword v177, v[180:181], off
	v_lshl_add_u64 v[180:181], v[138:139], 0, s[72:73]
	global_load_dword v152, v[180:181], off
	v_lshl_add_u64 v[180:181], v[136:137], 0, s[72:73]
	s_xor_b32 s72, s93, -4
	s_add_i32 s89, s89, 35
	s_add_i32 s93, s72, 0x400
	s_and_b64 s[72:73], s[38:39], exec
	s_cselect_b32 s72, s89, s93
	s_ashr_i32 s73, s72, 31
	s_lshl_b64 s[72:73], s[72:73], 14
	global_load_dword v178, v[180:181], off
	v_lshl_add_u64 v[180:181], v[138:139], 0, s[72:73]
	global_load_dword v154, v[180:181], off
	v_lshl_add_u64 v[180:181], v[136:137], 0, s[72:73]
	global_load_dword v179, v[180:181], off
	v_cndmask_b32_e64 v181, v147, v145, s[38:39]
	v_cndmask_b32_e64 v180, v146, v144, s[38:39]
	global_load_dwordx4 v[128:131], v[180:181], off
.Lscan1_top_nold:
	s_waitcnt lgkmcnt(0)
	s_barrier
	ds_read_b64 v[94:95], v0 offset:46848
	s_mov_b64 vcc, -1
	s_mov_b64 s[96:97], 0
	s_cmp_lt_i32 s6, 3
	s_mov_b64 s[72:73], 0
	s_cbranch_scc1 .LBB0_355
	s_cmp_gt_i32 s6, 4
	s_cbranch_scc0 .LBB0_346
	s_cmp_gt_i32 s6, 5
	s_cbranch_scc0 .LBB0_347
	s_cmp_eq_u32 s6, 6
	s_mov_b64 s[72:73], -1
	s_cbranch_scc0 .LBB0_345
	v_add_u32_e32 v2, 0x100, v0
	ds_read2st64_b64 v[100:103], v2 offset0:94 offset1:95
	ds_read2st64_b64 v[104:107], v2 offset0:96 offset1:97
	ds_read_b64 v[112:113], v0 offset:50432
	ds_read2st64_b64 v[108:111], v2 offset0:92 offset1:93
	s_mov_b64 s[72:73], 0
	s_waitcnt lgkmcnt(2)
	v_pk_mul_f32 v[4:5], v[102:103], v[104:105]
	s_nop 0
	v_rcp_f32_e32 v114, v4
	s_waitcnt lgkmcnt(0)
	v_pk_mul_f32 v[2:3], v[94:95], v[108:109]
	v_pk_mul_f32 v[98:99], v[106:107], v[112:113]
	v_pk_mul_f32 v[2:3], v[110:111], v[2:3]
	s_nop 0
	v_pk_mul_f32 v[96:97], v[100:101], v[2:3]
	v_rcp_f32_e32 v3, v5
	v_pk_mul_f32 v[96:97], v[102:103], v[96:97]
	v_min_f32_e32 v2, 0x79297b5a, v114
	v_pk_mul_f32 v[96:97], v[104:105], v[96:97]
	v_min_f32_e32 v3, 0x79297b5a, v3
	v_pk_mul_f32 v[100:101], v[96:97], v[106:107]
	s_nop 0
	v_pk_mul_f32 v[100:101], v[112:113], v[100:101]

.LBB0_370:
	s_cmp_gt_u32 s27, 30
	s_waitcnt lgkmcnt(0)
	s_barrier
	s_cbranch_scc1 .LBB0_372
.LBB0_372:
	s_and_b64 vcc, exec, s[86:87]
	v_add_u32_e32 v96, v160, v159
	s_cbranch_vccz .LBB0_374
	ds_read2_b64 v[2:5], v96 offset1:2
	v_cvt_pk_bf16_f32 v6, v16, v17
	v_cvt_pk_bf16_f32 v7, v18, v19
	v_cvt_pk_bf16_f32 v8, v20, v21
	v_cvt_pk_bf16_f32 v9, v22, v23
	s_waitcnt lgkmcnt(0)
	s_nop 0
	v_mfma_f32_32x32x16_bf16 v[80:95], v[2:5], v[6:9], 0
	ds_read2_b64 v[2:5], v96 offset0:4 offset1:6
	v_cvt_pk_bf16_f32 v6, v24, v25
	v_cvt_pk_bf16_f32 v7, v26, v27
	v_cvt_pk_bf16_f32 v8, v28, v29
	v_cvt_pk_bf16_f32 v9, v30, v31
	s_waitcnt lgkmcnt(0)
	s_nop 0
	v_mfma_f32_32x32x16_bf16 v[80:95], v[2:5], v[6:9], v[80:95]
	s_and_b64 vcc, exec, s[36:37]
	s_cbranch_vccz .LBB0_375
	s_branch .LBB0_376

.LBB0_392:
	s_andn2_b64 vcc, exec, s[34:35]
	s_waitcnt lgkmcnt(0)
	s_barrier
	s_cbranch_vccnz .LBB0_337
	v_add_u32_e32 v0, s80, v163
	v_cndmask_b32_e64 v0, v165, v0, s[38:39]
	v_add_u32_e32 v2, s88, v0
	v_ashrrev_i32_e32 v3, 31, v2
	v_lshlrev_b64 v[2:3], 11, v[2:3]
	v_add_u32_e32 v0, s9, v164
	v_lshl_add_u64 v[6:7], v[140:141], 0, v[2:3]
	ds_read_b128 v[2:5], v0 offset:50944
	s_waitcnt lgkmcnt(0)
	v_add_f32_e32 v2, v80, v2
	v_cvt_pk_bf16_f32 v2, v2, s0
	global_store_short v[6:7], v2, off
	v_add_f32_e32 v2, v81, v3
	v_cvt_pk_bf16_f32 v8, v2, s0
	v_lshl_add_u64 v[2:3], s[4:5], 1, v[6:7]
	v_add_f32_e32 v4, v82, v4
	global_store_short v[2:3], v8, off
	v_cvt_pk_bf16_f32 v4, v4, s0
	v_lshl_add_u64 v[2:3], v[2:3], 0, s[0:1]
	global_store_short v[2:3], v4, off
	v_add_f32_e32 v4, v83, v5
	v_cvt_pk_bf16_f32 v4, v4, s0
	v_lshl_add_u64 v[6:7], v[2:3], 0, s[0:1]
	global_store_short v[6:7], v4, off
	ds_read_b128 v[2:5], v0 offset:51968
	v_lshl_add_u64 v[6:7], v[6:7], 0, s[82:83]
	s_waitcnt lgkmcnt(0)
	v_add_f32_e32 v2, v84, v2
	v_cvt_pk_bf16_f32 v2, v2, s0
	global_store_short v[6:7], v2, off
	v_add_f32_e32 v2, v85, v3
	v_cvt_pk_bf16_f32 v8, v2, s0
	v_lshl_add_u64 v[2:3], v[6:7], 0, s[0:1]
	v_add_f32_e32 v4, v86, v4
	global_store_short v[2:3], v8, off
	v_cvt_pk_bf16_f32 v4, v4, s0
	v_lshl_add_u64 v[2:3], v[2:3], 0, s[0:1]
	global_store_short v[2:3], v4, off
	v_add_f32_e32 v4, v87, v5
	v_cvt_pk_bf16_f32 v4, v4, s0
	v_lshl_add_u64 v[6:7], v[2:3], 0, s[0:1]
	global_store_short v[6:7], v4, off
	ds_read_b128 v[2:5], v0 offset:52992
	v_lshl_add_u64 v[6:7], v[6:7], 0, s[82:83]
	s_waitcnt lgkmcnt(0)
	v_add_f32_e32 v2, v88, v2
	v_cvt_pk_bf16_f32 v2, v2, s0
	global_store_short v[6:7], v2, off
	v_add_f32_e32 v2, v89, v3
	v_cvt_pk_bf16_f32 v8, v2, s0
	v_lshl_add_u64 v[2:3], v[6:7], 0, s[0:1]
	v_add_f32_e32 v4, v90, v4
	global_store_short v[2:3], v8, off
	v_cvt_pk_bf16_f32 v4, v4, s0
	v_lshl_add_u64 v[2:3], v[2:3], 0, s[0:1]
	global_store_short v[2:3], v4, off
	v_add_f32_e32 v4, v91, v5
	v_cvt_pk_bf16_f32 v4, v4, s0
	v_lshl_add_u64 v[6:7], v[2:3], 0, s[0:1]
	global_store_short v[6:7], v4, off
	ds_read_b128 v[2:5], v0 offset:54016
	v_lshl_add_u64 v[6:7], v[6:7], 0, s[82:83]
	s_waitcnt lgkmcnt(0)
	v_add_f32_e32 v0, v92, v2
	v_cvt_pk_bf16_f32 v0, v0, s0
	global_store_short v[6:7], v0, off
	v_add_f32_e32 v0, v93, v3
	v_cvt_pk_bf16_f32 v0, v0, s0
	v_lshl_add_u64 v[2:3], v[6:7], 0, s[0:1]
	global_store_short v[2:3], v0, off
	v_add_f32_e32 v0, v94, v4
	v_cvt_pk_bf16_f32 v0, v0, s0
	v_lshl_add_u64 v[2:3], v[2:3], 0, s[0:1]
	global_store_short v[2:3], v0, off
	v_add_f32_e32 v0, v95, v5
	v_cvt_pk_bf16_f32 v0, v0, s0
	v_lshl_add_u64 v[2:3], v[2:3], 0, s[0:1]
	global_store_short v[2:3], v0, off
	s_add_i32 s80, s80, 32
	s_sub_i32 s26, s26, 32
	s_add_i32 s27, s27, 1
	v_subrev_u32_e32 v165, 32, v165
	v_lshl_add_u64 v[144:145], v[144:145], 0, 64
	s_cmpk_lg_i32 s80, 0x400
	v_lshl_add_u64 v[146:147], v[146:147], 0, s[22:23]
	s_cbranch_scc0 .LBB0_394
	s_waitcnt vmcnt(16)
	v_mov_b32_e32 v149, v176
	v_mov_b32_e32 v151, v177
	v_mov_b32_e32 v153, v178
	v_mov_b32_e32 v155, v179
	s_branch .Lscan1_top

.LBB0_412:
	s_add_i32 s80, s80, 32
	s_sub_i32 s26, s26, 32
	s_add_i32 s27, s27, 1
	v_subrev_u32_e32 v167, 32, v167
	v_lshl_add_u64 v[142:143], v[142:143], 0, 64
	s_cmpk_eq_i32 s80, 0x100
	v_lshl_add_u64 v[144:145], v[144:145], 0, s[22:23]
	s_cbranch_scc1 .LBB0_523
	s_waitcnt vmcnt(0)
	v_mov_b32_e32 v147, v176
	v_mov_b32_e32 v150, v177
	v_mov_b32_e32 v152, v178
	v_mov_b32_e32 v156, v179
	s_branch .Lscan2_top

.Lscan2_top:
	v_lshlrev_b32_e32 v0, 16, v146
	v_max_f32_e32 v0, v0, v0
	v_max_f32_e64 v4, -v157, -v157
	v_max_f32_e32 v0, v0, v4
	v_max_f32_e32 v5, v157, v157
	v_min_f32_e32 v0, v0, v5
	v_mul_f32_e32 v0, 0xbfb8aa3b, v0
	v_exp_f32_e32 v14, v0
	v_and_b32_e32 v0, 0xffff0000, v146
	v_max_f32_e32 v0, v0, v0
	v_max_f32_e32 v0, v0, v4
	v_min_f32_e32 v0, v0, v5
	v_mul_f32_e32 v0, 0xbfb8aa3b, v0
	v_exp_f32_e32 v15, v0
	v_add_f32_e32 v0, 1.0, v14
	v_rcp_f32_e32 v80, v0
	s_andn2_b64 vcc, exec, s[72:73]
	v_add_f32_e32 v0, 1.0, v15
	v_rcp_f32_e32 v81, v0
	v_pk_fma_f32 v[2:3], v[132:133], v[14:15], 1.0 op_sel_hi:[1,1,0]
	v_lshlrev_b32_e32 v0, 16, v149
	v_max_f32_e32 v0, v0, v0
	v_pk_mul_f32 v[10:11], v[80:81], v[2:3]
	v_lshlrev_b32_e32 v2, 16, v151
	v_max_f32_e32 v2, v2, v2
	v_max_f32_e32 v2, v2, v4
	v_min_f32_e32 v2, v2, v5
	v_mul_f32_e32 v2, 0xbfb8aa3b, v2
	v_exp_f32_e32 v86, v2
	v_and_b32_e32 v2, 0xffff0000, v151
	v_max_f32_e32 v2, v2, v2
	v_max_f32_e32 v2, v2, v4
	v_max_f32_e32 v0, v0, v4
	v_min_f32_e32 v2, v2, v5
	v_min_f32_e32 v0, v0, v5
	v_mul_f32_e32 v2, 0xbfb8aa3b, v2
	v_mul_f32_e32 v0, 0xbfb8aa3b, v0
	v_exp_f32_e32 v87, v2
	v_lshlrev_b32_e32 v2, 16, v153
	v_exp_f32_e32 v82, v0
	v_and_b32_e32 v0, 0xffff0000, v149
	v_max_f32_e32 v2, v2, v2
	v_max_f32_e32 v0, v0, v0
	v_max_f32_e32 v2, v2, v4
	v_max_f32_e32 v0, v0, v4
	v_min_f32_e32 v2, v2, v5
	v_min_f32_e32 v0, v0, v5
	v_mul_f32_e32 v2, 0xbfb8aa3b, v2
	v_mul_f32_e32 v0, 0xbfb8aa3b, v0
	v_exp_f32_e32 v90, v2
	v_and_b32_e32 v2, 0xffff0000, v153
	v_exp_f32_e32 v83, v0
	v_max_f32_e32 v2, v2, v2
	v_max_f32_e32 v2, v2, v4
	v_min_f32_e32 v2, v2, v5
	v_add_f32_e32 v0, 1.0, v82
	v_mul_f32_e32 v2, 0xbfb8aa3b, v2
	v_rcp_f32_e32 v84, v0
	v_add_f32_e32 v0, 1.0, v83
	v_exp_f32_e32 v91, v2
	v_rcp_f32_e32 v85, v0
	v_add_f32_e32 v0, 1.0, v86
	v_rcp_f32_e32 v88, v0
	v_add_f32_e32 v0, 1.0, v87
	v_rcp_f32_e32 v89, v0
	v_add_f32_e32 v0, 1.0, v90
	v_rcp_f32_e32 v92, v0
	v_add_f32_e32 v0, 1.0, v91
	v_pk_fma_f32 v[2:3], v[132:133], v[82:83], 1.0 op_sel_hi:[1,1,0]
	v_rcp_f32_e32 v93, v0
	v_pk_mul_f32 v[2:3], v[84:85], v[2:3]
	s_nop 0
	v_pk_mul_f32 v[12:13], v[10:11], v[2:3]
	v_pk_fma_f32 v[2:3], v[132:133], v[86:87], 1.0 op_sel_hi:[1,1,0]
	s_nop 0
	v_pk_mul_f32 v[2:3], v[88:89], v[2:3]
	s_nop 0
	v_pk_mul_f32 v[8:9], v[12:13], v[2:3]
	v_pk_fma_f32 v[2:3], v[132:133], v[90:91], 1.0 op_sel_hi:[1,1,0]
	s_nop 0
	v_pk_mul_f32 v[2:3], v[92:93], v[2:3]
	s_nop 0
	v_pk_mul_f32 v[6:7], v[8:9], v[2:3]
	v_mov_b64_e32 v[2:3], v[128:129]
	v_mov_b64_e32 v[4:5], v[130:131]
	ds_write_b64 v158, v[6:7] offset:46848
	s_cbranch_vccnz .LBB0_415
	v_alignbit_b32 v2, v131, v131, 16
	v_alignbit_b32 v3, v130, v130, 16
	v_alignbit_b32 v4, v129, v129, 16
	v_alignbit_b32 v5, v128, v128, 16
.LBB0_415:
	v_add_u32_e32 v0, v160, v159
	ds_write_b128 v168, v[2:5] offset:36096
	s_cmp_gt_u32 s27, 6
	s_cbranch_scc1 .Lscan2_top_nold
	s_add_i32 s4, s21, s80
	s_add_i32 s5, s4, 32
	s_and_b64 s[0:1], s[36:37], exec
	s_cselect_b32 s0, s5, s26
	s_ashr_i32 s1, s0, 31
	s_lshl_b64 s[0:1], s[0:1], 14
	v_lshl_add_u64 v[180:181], v[136:137], 0, s[0:1]
	global_load_dword v146, v[180:181], off
	v_lshl_add_u64 v[180:181], v[134:135], 0, s[0:1]
	s_xor_b32 s0, s5, -2
	s_add_i32 s70, s4, 33
	s_add_i32 s71, s0, 0x100
	s_and_b64 s[0:1], s[36:37], exec
	s_cselect_b32 s0, s70, s71
	s_ashr_i32 s1, s0, 31
	s_lshl_b64 s[0:1], s[0:1], 14
	global_load_dword v176, v[180:181], off
	v_lshl_add_u64 v[180:181], v[136:137], 0, s[0:1]
	global_load_dword v149, v[180:181], off
	v_lshl_add_u64 v[180:181], v[134:135], 0, s[0:1]
	s_xor_b32 s0, s5, -3
	s_add_i32 s70, s4, 34
	s_add_i32 s71, s0, 0x100
	s_and_b64 s[0:1], s[36:37], exec
	s_cselect_b32 s0, s70, s71
	s_ashr_i32 s1, s0, 31
	s_lshl_b64 s[0:1], s[0:1], 14
	global_load_dword v177, v[180:181], off
	v_lshl_add_u64 v[180:181], v[136:137], 0, s[0:1]
	global_load_dword v151, v[180:181], off
	v_lshl_add_u64 v[180:181], v[134:135], 0, s[0:1]
	s_xor_b32 s0, s5, -4
	s_add_i32 s4, s4, 35
	s_add_i32 s5, s0, 0x100
	s_and_b64 s[0:1], s[36:37], exec
	s_cselect_b32 s0, s4, s5
	s_ashr_i32 s1, s0, 31
	s_lshl_b64 s[0:1], s[0:1], 14
	global_load_dword v178, v[180:181], off
	v_lshl_add_u64 v[180:181], v[136:137], 0, s[0:1]
	global_load_dword v153, v[180:181], off
	v_lshl_add_u64 v[180:181], v[134:135], 0, s[0:1]
	global_load_dword v179, v[180:181], off
	v_cndmask_b32_e64 v181, v145, v143, s[36:37]
	v_cndmask_b32_e64 v180, v144, v142, s[36:37]
	global_load_dwordx4 v[128:131], v[180:181], off
.Lscan2_top_nold:
	s_waitcnt lgkmcnt(0)
	s_barrier
	ds_read_b64 v[94:95], v0 offset:46848
	s_mov_b64 s[70:71], -1
	s_mov_b64 s[4:5], 0
	s_cmp_lt_i32 s81, 3
	s_mov_b64 s[0:1], 0
	s_cbranch_scc1 .LBB0_430
	s_cmp_gt_i32 s81, 4
	s_cbranch_scc0 .LBB0_421
	s_cmp_gt_i32 s81, 5
	s_cbranch_scc0 .LBB0_422
	s_cmp_eq_u32 s81, 6
	s_mov_b64 s[0:1], -1
	s_cbranch_scc0 .LBB0_420
	v_add_u32_e32 v2, 0x100, v0
	ds_read2st64_b64 v[100:103], v2 offset0:94 offset1:95
	ds_read2st64_b64 v[104:107], v2 offset0:96 offset1:97
	ds_read_b64 v[112:113], v0 offset:50432
	ds_read2st64_b64 v[108:111], v2 offset0:92 offset1:93
	s_mov_b64 s[0:1], 0
	s_waitcnt lgkmcnt(2)
	v_pk_mul_f32 v[4:5], v[102:103], v[104:105]
	s_nop 0
	v_rcp_f32_e32 v114, v4
	s_waitcnt lgkmcnt(0)
	v_pk_mul_f32 v[2:3], v[94:95], v[108:109]
	v_pk_mul_f32 v[98:99], v[106:107], v[112:113]
	v_pk_mul_f32 v[2:3], v[110:111], v[2:3]
	s_nop 0
	v_pk_mul_f32 v[96:97], v[100:101], v[2:3]
	v_rcp_f32_e32 v3, v5
	v_pk_mul_f32 v[96:97], v[102:103], v[96:97]
	v_min_f32_e32 v2, 0x79297b5a, v114
	v_pk_mul_f32 v[96:97], v[104:105], v[96:97]
	v_min_f32_e32 v3, 0x79297b5a, v3
	v_pk_mul_f32 v[100:101], v[96:97], v[106:107]
	s_nop 0
	v_pk_mul_f32 v[100:101], v[112:113], v[100:101]

.LBB0_445:
	s_cmp_gt_u32 s27, 6
	s_waitcnt lgkmcnt(0)
	s_barrier
	s_cbranch_scc1 .LBB0_447
.LBB0_447:
	s_and_b64 vcc, exec, s[90:91]
	v_add_u32_e32 v96, v162, v161
	s_cbranch_vccz .LBB0_449
	ds_read2_b64 v[2:5], v96 offset1:2
	v_cvt_pk_bf16_f32 v6, v32, v33
	v_cvt_pk_bf16_f32 v7, v34, v35
	v_cvt_pk_bf16_f32 v8, v36, v37
	v_cvt_pk_bf16_f32 v9, v38, v39
	s_waitcnt lgkmcnt(0)
	s_nop 0
	v_mfma_f32_32x32x16_bf16 v[80:95], v[2:5], v[6:9], 0
	ds_read2_b64 v[2:5], v96 offset0:4 offset1:6
	v_cvt_pk_bf16_f32 v6, v40, v41
	v_cvt_pk_bf16_f32 v7, v42, v43
	v_cvt_pk_bf16_f32 v8, v44, v45
	v_cvt_pk_bf16_f32 v9, v46, v47
	s_waitcnt lgkmcnt(0)
	s_nop 0
	v_mfma_f32_32x32x16_bf16 v[80:95], v[2:5], v[6:9], v[80:95]
	v_cndmask_b32_e64 v0, 0, 1, s[86:87]
	v_cmp_ne_u32_e64 s[70:71], 1, v0
	s_andn2_b64 vcc, exec, s[86:87]
	s_cbranch_vccz .LBB0_450
	s_branch .LBB0_451

.LBB0_467:
	s_andn2_b64 vcc, exec, s[90:91]
	s_waitcnt lgkmcnt(0)
	s_barrier
	s_cbranch_vccnz .LBB0_412
	v_add_u32_e32 v0, s80, v165
	v_cndmask_b32_e64 v0, v167, v0, s[36:37]
	v_add_u32_e32 v2, s6, v0
	v_ashrrev_i32_e32 v3, 31, v2
	v_lshlrev_b64 v[2:3], 11, v[2:3]
	v_add_u32_e32 v0, s9, v166
	v_lshl_add_u64 v[6:7], v[138:139], 0, v[2:3]
	ds_read_b128 v[2:5], v0 offset:50944
	s_waitcnt lgkmcnt(0)
	v_add_f32_e32 v2, v80, v2
	v_cvt_pk_bf16_f32 v2, v2, s0
	global_store_short v[6:7], v2, off
	v_add_f32_e32 v2, v81, v3
	v_cvt_pk_bf16_f32 v8, v2, s0
	v_lshl_add_u64 v[2:3], s[24:25], 1, v[6:7]
	v_add_f32_e32 v4, v82, v4
	global_store_short v[2:3], v8, off
	v_cvt_pk_bf16_f32 v4, v4, s0
	v_lshl_add_u64 v[2:3], v[2:3], 0, s[30:31]
	global_store_short v[2:3], v4, off
	v_add_f32_e32 v4, v83, v5
	v_cvt_pk_bf16_f32 v4, v4, s0
	v_lshl_add_u64 v[6:7], v[2:3], 0, s[30:31]
	global_store_short v[6:7], v4, off
	ds_read_b128 v[2:5], v0 offset:51968
	v_lshl_add_u64 v[6:7], v[6:7], 0, s[34:35]
	s_waitcnt lgkmcnt(0)
	v_add_f32_e32 v2, v84, v2
	v_cvt_pk_bf16_f32 v2, v2, s0
	global_store_short v[6:7], v2, off
	v_add_f32_e32 v2, v85, v3
	v_cvt_pk_bf16_f32 v8, v2, s0
	v_lshl_add_u64 v[2:3], v[6:7], 0, s[30:31]
	v_add_f32_e32 v4, v86, v4
	global_store_short v[2:3], v8, off
	v_cvt_pk_bf16_f32 v4, v4, s0
	v_lshl_add_u64 v[2:3], v[2:3], 0, s[30:31]
	global_store_short v[2:3], v4, off
	v_add_f32_e32 v4, v87, v5
	v_cvt_pk_bf16_f32 v4, v4, s0
	v_lshl_add_u64 v[6:7], v[2:3], 0, s[30:31]
	global_store_short v[6:7], v4, off
	ds_read_b128 v[2:5], v0 offset:52992
	v_lshl_add_u64 v[6:7], v[6:7], 0, s[34:35]
	s_waitcnt lgkmcnt(0)
	v_add_f32_e32 v2, v88, v2
	v_cvt_pk_bf16_f32 v2, v2, s0
	global_store_short v[6:7], v2, off
	v_add_f32_e32 v2, v89, v3
	v_cvt_pk_bf16_f32 v8, v2, s0
	v_lshl_add_u64 v[2:3], v[6:7], 0, s[30:31]
	v_add_f32_e32 v4, v90, v4
	global_store_short v[2:3], v8, off
	v_cvt_pk_bf16_f32 v4, v4, s0
	v_lshl_add_u64 v[2:3], v[2:3], 0, s[30:31]
	global_store_short v[2:3], v4, off
	v_add_f32_e32 v4, v91, v5
	v_cvt_pk_bf16_f32 v4, v4, s0
	v_lshl_add_u64 v[6:7], v[2:3], 0, s[30:31]
	global_store_short v[6:7], v4, off
	ds_read_b128 v[2:5], v0 offset:54016
	v_lshl_add_u64 v[6:7], v[6:7], 0, s[34:35]
	s_waitcnt lgkmcnt(0)
	v_add_f32_e32 v0, v92, v2
	v_cvt_pk_bf16_f32 v0, v0, s0
	global_store_short v[6:7], v0, off
	v_add_f32_e32 v0, v93, v3
	v_cvt_pk_bf16_f32 v0, v0, s0
	v_lshl_add_u64 v[2:3], v[6:7], 0, s[30:31]
	global_store_short v[2:3], v0, off
	v_add_f32_e32 v0, v94, v4
	v_cvt_pk_bf16_f32 v0, v0, s0
	v_lshl_add_u64 v[2:3], v[2:3], 0, s[30:31]
	global_store_short v[2:3], v0, off
	v_add_f32_e32 v0, v95, v5
	v_cvt_pk_bf16_f32 v0, v0, s0
	v_lshl_add_u64 v[2:3], v[2:3], 0, s[30:31]
	global_store_short v[2:3], v0, off
	s_add_i32 s80, s80, 32
	s_sub_i32 s26, s26, 32
	s_add_i32 s27, s27, 1
	v_subrev_u32_e32 v167, 32, v167
	v_lshl_add_u64 v[142:143], v[142:143], 0, 64
	s_cmpk_eq_i32 s80, 0x100
	v_lshl_add_u64 v[144:145], v[144:145], 0, s[22:23]
	s_cbranch_scc1 .LBB0_523
	s_waitcnt vmcnt(16)
	v_mov_b32_e32 v147, v176
	v_mov_b32_e32 v150, v177
	v_mov_b32_e32 v152, v178
	v_mov_b32_e32 v156, v179
	s_branch .Lscan2_top
